# v67 + back-edge rotation of the three GEMM K-loops: steady path carries its own latch (updates + tail test before the barrier, single taken branch after it)
# baseline (speedup 1.0000x reference)
; #define MFMA32(a, b, c) __builtin_amdgcn_mfma_f32_32x32x16_bf16((a), (b), (c), 0, 0, 0)
; #define G_LOAD(KT) do { const int k0_ = (KT) << 6; _Pragma("unroll") for (int p = 0; p < 4; ++p) { \
;     ra[p] = *(const u32x4*)(ap + (size_t)(64 * p) * lda + k0_); rb[p] = *(const u32x4*)(bp + (size_t)(64 * p) * ldb + k0_); } } while (0)
; template <bool SWAP, bool SSQ, bool ZERO = true>
; DI void gemm_main(const u16* __restrict__ A, int lda, const u16* __restrict__ Bt, int ldb, int K, char* lds,
;                   f32x16 (&acc)[4][2], float* rs_lds) {
;     ...
;   for (int kt = 0; kt < nk; ++kt) {
;     const int st = (kt & 1) * 2 * G_TILE;
;     {
;       bf16x8 fa[2][4], fb[2][2];
; #pragma unroll
;       for (int i = 0; i < 4; ++i) fa[0][i] = *(const bf16x8*)(abase + st + i * 32 * GS);
; #pragma unroll
;       for (int i = 0; i < 2; ++i) fb[0][i] = *(const bf16x8*)(bbase + st + i * 32 * GS);
; #pragma unroll
;       for (int ks = 0; ks < 4; ++ks) {
;         if (ks + 1 < 4) {
; #pragma unroll
;           for (int i = 0; i < 4; ++i) fa[(ks + 1) & 1][i] = *(const bf16x8*)(abase + st + i * 32 * GS + (ks + 1) * 32);
; #pragma unroll
;           for (int i = 0; i < 2; ++i) fb[(ks + 1) & 1][i] = *(const bf16x8*)(bbase + st + i * 32 * GS + (ks + 1) * 32);
;         }
;         __builtin_amdgcn_sched_barrier(0);
;         __builtin_amdgcn_s_setprio(1);
; #pragma unroll
;         for (int mt = 0; mt < 4; ++mt)
; #pragma unroll
;           for (int nt = 0; nt < 2; ++nt)
;             acc[mt][nt] = SWAP ? MFMA32(fb[ks & 1][nt], fa[ks & 1][mt], acc[mt][nt]) : MFMA32(fa[ks & 1][mt], fb[ks & 1][nt], acc[mt][nt]);
;         __builtin_amdgcn_s_setprio(0);
;         __builtin_amdgcn_sched_barrier(0);
;       }
;     }
;     if (kt + 1 < nk) G_WRITE((kt + 1) & 1);
;     if (kt + 2 < nk) G_LOAD(kt + 2);
;     __syncthreads();
;   }
.Lrot92_body:
	ds_read_b128 v[204:207], v165 offset:36864
	ds_read_b128 v[172:175], v0
	ds_read_b128 v[212:215], v165 offset:41472
	ds_read_b128 v[180:183], v0 offset:4608
	ds_read_b128 v[188:191], v0 offset:9216
	ds_read_b128 v[196:199], v0 offset:13824
	s_setprio 1
	s_waitcnt lgkmcnt(4)
	v_mfma_f32_32x32x16_bf16 v[114:129], v[204:207], v[172:175], v[114:129]
	ds_read_b128 v[208:211], v165 offset:36896
	s_waitcnt lgkmcnt(4)
	v_mfma_f32_32x32x16_bf16 v[98:113], v[212:215], v[172:175], v[98:113]
	ds_read_b128 v[176:179], v0 offset:32
	ds_read_b128 v[172:175], v0 offset:64
	s_waitcnt lgkmcnt(5)
	v_mfma_f32_32x32x16_bf16 v[82:97], v[204:207], v[180:183], v[82:97]
	ds_read_b128 v[216:219], v165 offset:41504
	v_mfma_f32_32x32x16_bf16 v[66:81], v[212:215], v[180:183], v[66:81]
	ds_read_b128 v[184:187], v0 offset:4640
	ds_read_b128 v[180:183], v0 offset:4672
	s_waitcnt lgkmcnt(7)
	v_mfma_f32_32x32x16_bf16 v[50:65], v[204:207], v[188:191], v[50:65]
	ds_read_b128 v[192:195], v0 offset:9248
	v_mfma_f32_32x32x16_bf16 v[34:49], v[212:215], v[188:191], v[34:49]
	ds_read_b128 v[200:203], v0 offset:13856
	ds_read_b128 v[188:191], v0 offset:9280
	s_waitcnt lgkmcnt(9)
	v_mfma_f32_32x32x16_bf16 v[18:33], v[204:207], v[196:199], v[18:33]
	ds_read_b128 v[204:207], v165 offset:36928
	v_mfma_f32_32x32x16_bf16 v[2:17], v[212:215], v[196:199], v[2:17]
	ds_read_b128 v[212:215], v165 offset:41536
	ds_read_b128 v[196:199], v0 offset:13888
	s_setprio 0
	s_setprio 1
	s_waitcnt lgkmcnt(10)
	v_mfma_f32_32x32x16_bf16 v[114:129], v[208:211], v[176:179], v[114:129]
	s_waitcnt lgkmcnt(8)
	v_mfma_f32_32x32x16_bf16 v[98:113], v[216:219], v[176:179], v[98:113]
	ds_read_b128 v[176:179], v0 offset:96
	s_waitcnt lgkmcnt(8)
	v_mfma_f32_32x32x16_bf16 v[82:97], v[208:211], v[184:187], v[82:97]
	v_mfma_f32_32x32x16_bf16 v[66:81], v[216:219], v[184:187], v[66:81]
	ds_read_b128 v[184:187], v0 offset:4704
	s_waitcnt lgkmcnt(7)
	v_mfma_f32_32x32x16_bf16 v[50:65], v[208:211], v[192:195], v[50:65]
	v_mfma_f32_32x32x16_bf16 v[34:49], v[216:219], v[192:195], v[34:49]
	ds_read_b128 v[192:195], v0 offset:9312
	s_waitcnt lgkmcnt(7)
	v_mfma_f32_32x32x16_bf16 v[18:33], v[208:211], v[200:203], v[18:33]
	ds_read_b128 v[208:211], v165 offset:36960
	v_mfma_f32_32x32x16_bf16 v[2:17], v[216:219], v[200:203], v[2:17]
	ds_read_b128 v[216:219], v165 offset:41568
	ds_read_b128 v[200:203], v0 offset:13920
	s_setprio 0
	s_setprio 1
	s_waitcnt lgkmcnt(8)
	v_mfma_f32_32x32x16_bf16 v[114:129], v[204:207], v[172:175], v[114:129]
	s_waitcnt lgkmcnt(7)
	v_mfma_f32_32x32x16_bf16 v[98:113], v[212:215], v[172:175], v[98:113]
	v_mfma_f32_32x32x16_bf16 v[82:97], v[204:207], v[180:183], v[82:97]
	v_mfma_f32_32x32x16_bf16 v[66:81], v[212:215], v[180:183], v[66:81]
	s_and_b32 s62, s53, 2
	s_mul_i32 s62, s62, 0x9000
	v_add_u32_e32 v240, s62, v162
	v_lshl_add_u64 v[220:221], v[168:169], 0, s[86:87]
	v_lshl_add_u64 v[234:235], v[166:167], 0, s[86:87]
	v_mfma_f32_32x32x16_bf16 v[50:65], v[204:207], v[188:191], v[50:65]
	s_waitcnt vmcnt(7)
	ds_write_b128 v240, v[130:133]
	global_load_dwordx4 v[130:133], v[220:221], off offset:256
	v_add_co_u32_e32 v220, vcc, 0x40000, v220
	v_mfma_f32_32x32x16_bf16 v[34:49], v[212:215], v[188:191], v[34:49]
	s_waitcnt vmcnt(7)
	ds_write_b128 v240, v[134:137] offset:36864
	v_addc_co_u32_e32 v221, vcc, 0, v221, vcc
	global_load_dwordx4 v[134:137], v[234:235], off offset:256
	v_add_co_u32_e32 v234, vcc, 0x40000, v234
	s_waitcnt lgkmcnt(8)
	v_mfma_f32_32x32x16_bf16 v[18:33], v[204:207], v[196:199], v[18:33]
	s_waitcnt vmcnt(7)
	ds_write_b128 v240, v[138:141] offset:9216
	v_addc_co_u32_e32 v235, vcc, 0, v235, vcc
	global_load_dwordx4 v[138:141], v[220:221], off offset:256
	v_add_co_u32_e32 v220, vcc, 0x40000, v220
	v_mfma_f32_32x32x16_bf16 v[2:17], v[212:215], v[196:199], v[2:17]
	s_waitcnt vmcnt(7)
	ds_write_b128 v240, v[142:145] offset:46080
	v_addc_co_u32_e32 v221, vcc, 0, v221, vcc
	global_load_dwordx4 v[142:145], v[234:235], off offset:256
	v_add_co_u32_e32 v234, vcc, 0x40000, v234
	s_setprio 0
	s_setprio 1
	s_waitcnt lgkmcnt(6)
	v_mfma_f32_32x32x16_bf16 v[114:129], v[208:211], v[176:179], v[114:129]
	s_waitcnt vmcnt(7)
	ds_write_b128 v240, v[146:149] offset:18432
	v_addc_co_u32_e32 v235, vcc, 0, v235, vcc
	global_load_dwordx4 v[146:149], v[220:221], off offset:256
	v_add_co_u32_e32 v220, vcc, 0x40000, v220
	s_waitcnt lgkmcnt(6)
	v_mfma_f32_32x32x16_bf16 v[98:113], v[216:219], v[176:179], v[98:113]
	s_waitcnt vmcnt(7)
	ds_write_b128 v240, v[150:153] offset:55296
	v_addc_co_u32_e32 v221, vcc, 0, v221, vcc
	global_load_dwordx4 v[150:153], v[234:235], off offset:256
	v_add_co_u32_e32 v234, vcc, 0x40000, v234
	v_mfma_f32_32x32x16_bf16 v[82:97], v[208:211], v[184:187], v[82:97]
	s_waitcnt vmcnt(7)
	ds_write_b128 v240, v[154:157] offset:27648
	v_addc_co_u32_e32 v235, vcc, 0, v235, vcc
	global_load_dwordx4 v[154:157], v[220:221], off offset:256
	v_mfma_f32_32x32x16_bf16 v[66:81], v[216:219], v[184:187], v[66:81]
	s_waitcnt vmcnt(7)
	ds_write_b128 v240, v[158:161] offset:64512
	global_load_dwordx4 v[158:161], v[234:235], off offset:256
	v_mfma_f32_32x32x16_bf16 v[50:65], v[208:211], v[192:195], v[50:65]
	v_mfma_f32_32x32x16_bf16 v[34:49], v[216:219], v[192:195], v[34:49]
	s_waitcnt lgkmcnt(8)
	v_mfma_f32_32x32x16_bf16 v[18:33], v[208:211], v[200:203], v[18:33]
	v_mfma_f32_32x32x16_bf16 v[2:17], v[216:219], v[200:203], v[2:17]
	s_setprio 0
	s_add_u32 s86, s86, 0x80
	s_addc_u32 s87, s87, 0
	s_add_i32 s53, s53, 2
	s_add_i32 s52, s52, 1
	s_add_i32 s62, s53, -2
	s_and_b32 s62, s62, 2
	s_mul_i32 s62, s62, 0x9000
	v_add_u32_e32 v0, s62, v164
	v_add_u32_e32 v165, s62, v163
	s_cmp_gt_u32 s52, 29
	s_waitcnt lgkmcnt(0)
	s_barrier
	s_cbranch_scc0 .Lrot92_body

; #define MFMA32(a, b, c) __builtin_amdgcn_mfma_f32_32x32x16_bf16((a), (b), (c), 0, 0, 0)
; #define G_LOAD(KT) do { const int k0_ = (KT) << 6; _Pragma("unroll") for (int p = 0; p < 4; ++p) { \
;     ra[p] = *(const u32x4*)(ap + (size_t)(64 * p) * lda + k0_); rb[p] = *(const u32x4*)(bp + (size_t)(64 * p) * ldb + k0_); } } while (0)
; template <bool SWAP, bool SSQ, bool ZERO = true>
; DI void gemm_main(const u16* __restrict__ A, int lda, const u16* __restrict__ Bt, int ldb, int K, char* lds,
;                   f32x16 (&acc)[4][2], float* rs_lds) {
;     ...
;   for (int kt = 0; kt < nk; ++kt) {
;     const int st = (kt & 1) * 2 * G_TILE;
;     {
;       bf16x8 fa[2][4], fb[2][2];
; #pragma unroll
;       for (int i = 0; i < 4; ++i) fa[0][i] = *(const bf16x8*)(abase + st + i * 32 * GS);
; #pragma unroll
;       for (int i = 0; i < 2; ++i) fb[0][i] = *(const bf16x8*)(bbase + st + i * 32 * GS);
; #pragma unroll
;       for (int ks = 0; ks < 4; ++ks) {
;         if (ks + 1 < 4) {
; #pragma unroll
;           for (int i = 0; i < 4; ++i) fa[(ks + 1) & 1][i] = *(const bf16x8*)(abase + st + i * 32 * GS + (ks + 1) * 32);
; #pragma unroll
;           for (int i = 0; i < 2; ++i) fb[(ks + 1) & 1][i] = *(const bf16x8*)(bbase + st + i * 32 * GS + (ks + 1) * 32);
;         }
;         __builtin_amdgcn_sched_barrier(0);
;         __builtin_amdgcn_s_setprio(1);
; #pragma unroll
;         for (int mt = 0; mt < 4; ++mt)
; #pragma unroll
;           for (int nt = 0; nt < 2; ++nt)
;             acc[mt][nt] = SWAP ? MFMA32(fb[ks & 1][nt], fa[ks & 1][mt], acc[mt][nt]) : MFMA32(fa[ks & 1][mt], fb[ks & 1][nt], acc[mt][nt]);
;         __builtin_amdgcn_s_setprio(0);
;         __builtin_amdgcn_sched_barrier(0);
;       }
;     }
;     if (kt + 1 < nk) G_WRITE((kt + 1) & 1);
;     if (kt + 2 < nk) G_LOAD(kt + 2);
;     __syncthreads();
;   }
.Lrot119_body:
	ds_read_b128 v[170:173], v0
	ds_read_b128 v[202:205], v165 offset:36864
	ds_read_b128 v[210:213], v165 offset:41472
	ds_read_b128 v[178:181], v0 offset:4608
	ds_read_b128 v[186:189], v0 offset:9216
	ds_read_b128 v[194:197], v0 offset:13824
	s_setprio 1
	s_waitcnt lgkmcnt(4)
	v_mfma_f32_32x32x16_bf16 v[114:129], v[170:173], v[202:205], v[114:129]
	ds_read_b128 v[174:177], v0 offset:32
	s_waitcnt lgkmcnt(4)
	v_mfma_f32_32x32x16_bf16 v[98:113], v[170:173], v[210:213], v[98:113]
	ds_read_b128 v[206:209], v165 offset:36896
	ds_read_b128 v[170:173], v0 offset:64
	s_waitcnt lgkmcnt(5)
	v_mfma_f32_32x32x16_bf16 v[82:97], v[178:181], v[202:205], v[82:97]
	ds_read_b128 v[214:217], v165 offset:41504
	v_mfma_f32_32x32x16_bf16 v[66:81], v[178:181], v[210:213], v[66:81]
	ds_read_b128 v[182:185], v0 offset:4640
	ds_read_b128 v[178:181], v0 offset:4672
	s_waitcnt lgkmcnt(7)
	v_mfma_f32_32x32x16_bf16 v[50:65], v[186:189], v[202:205], v[50:65]
	ds_read_b128 v[190:193], v0 offset:9248
	v_mfma_f32_32x32x16_bf16 v[34:49], v[186:189], v[210:213], v[34:49]
	ds_read_b128 v[198:201], v0 offset:13856
	ds_read_b128 v[186:189], v0 offset:9280
	s_waitcnt lgkmcnt(9)
	v_mfma_f32_32x32x16_bf16 v[18:33], v[194:197], v[202:205], v[18:33]
	ds_read_b128 v[202:205], v165 offset:36928
	v_mfma_f32_32x32x16_bf16 v[2:17], v[194:197], v[210:213], v[2:17]
	ds_read_b128 v[210:213], v165 offset:41536
	ds_read_b128 v[194:197], v0 offset:13888
	s_setprio 0
	s_setprio 1
	s_waitcnt lgkmcnt(10)
	v_mfma_f32_32x32x16_bf16 v[114:129], v[174:177], v[206:209], v[114:129]
	s_waitcnt lgkmcnt(8)
	v_mfma_f32_32x32x16_bf16 v[98:113], v[174:177], v[214:217], v[98:113]
	ds_read_b128 v[174:177], v0 offset:96
	s_waitcnt lgkmcnt(8)
	v_mfma_f32_32x32x16_bf16 v[82:97], v[182:185], v[206:209], v[82:97]
	v_mfma_f32_32x32x16_bf16 v[66:81], v[182:185], v[214:217], v[66:81]
	ds_read_b128 v[182:185], v0 offset:4704
	s_waitcnt lgkmcnt(7)
	v_mfma_f32_32x32x16_bf16 v[50:65], v[190:193], v[206:209], v[50:65]
	v_mfma_f32_32x32x16_bf16 v[34:49], v[190:193], v[214:217], v[34:49]
	ds_read_b128 v[190:193], v0 offset:9312
	s_waitcnt lgkmcnt(7)
	v_mfma_f32_32x32x16_bf16 v[18:33], v[198:201], v[206:209], v[18:33]
	ds_read_b128 v[206:209], v165 offset:36960
	v_mfma_f32_32x32x16_bf16 v[2:17], v[198:201], v[214:217], v[2:17]
	ds_read_b128 v[214:217], v165 offset:41568
	ds_read_b128 v[198:201], v0 offset:13920
	s_setprio 0
	s_setprio 1
	s_waitcnt lgkmcnt(8)
	v_mfma_f32_32x32x16_bf16 v[114:129], v[170:173], v[202:205], v[114:129]
	s_waitcnt lgkmcnt(7)
	v_mfma_f32_32x32x16_bf16 v[98:113], v[170:173], v[210:213], v[98:113]
	v_mfma_f32_32x32x16_bf16 v[82:97], v[178:181], v[202:205], v[82:97]
	v_mfma_f32_32x32x16_bf16 v[66:81], v[178:181], v[210:213], v[66:81]
	s_and_b32 s52, s4, 2
	s_mul_i32 s52, s52, 0x9000
	v_add_u32_e32 v240, s52, v162
	v_lshl_add_u64 v[220:221], v[168:169], 0, s[0:1]
	v_lshl_add_u64 v[234:235], v[166:167], 0, s[0:1]
	v_mfma_f32_32x32x16_bf16 v[50:65], v[186:189], v[202:205], v[50:65]
	s_waitcnt vmcnt(7)
	ds_write_b128 v240, v[130:133]
	global_load_dwordx4 v[130:133], v[220:221], off offset:256
	v_add_co_u32_e32 v220, vcc, 0x40000, v220
	v_mfma_f32_32x32x16_bf16 v[34:49], v[186:189], v[210:213], v[34:49]
	s_waitcnt vmcnt(7)
	ds_write_b128 v240, v[134:137] offset:36864
	v_addc_co_u32_e32 v221, vcc, 0, v221, vcc
	global_load_dwordx4 v[134:137], v[234:235], off offset:256
	v_add_co_u32_e32 v234, vcc, 0x40000, v234
	s_waitcnt lgkmcnt(8)
	v_mfma_f32_32x32x16_bf16 v[18:33], v[194:197], v[202:205], v[18:33]
	s_waitcnt vmcnt(7)
	ds_write_b128 v240, v[138:141] offset:9216
	v_addc_co_u32_e32 v235, vcc, 0, v235, vcc
	global_load_dwordx4 v[138:141], v[220:221], off offset:256
	v_add_co_u32_e32 v220, vcc, 0x40000, v220
	v_mfma_f32_32x32x16_bf16 v[2:17], v[194:197], v[210:213], v[2:17]
	s_waitcnt vmcnt(7)
	ds_write_b128 v240, v[142:145] offset:46080
	v_addc_co_u32_e32 v221, vcc, 0, v221, vcc
	global_load_dwordx4 v[142:145], v[234:235], off offset:256
	v_add_co_u32_e32 v234, vcc, 0x40000, v234
	s_setprio 0
	s_setprio 1
	s_waitcnt lgkmcnt(6)
	v_mfma_f32_32x32x16_bf16 v[114:129], v[174:177], v[206:209], v[114:129]
	s_waitcnt vmcnt(7)
	ds_write_b128 v240, v[146:149] offset:18432
	v_addc_co_u32_e32 v235, vcc, 0, v235, vcc
	global_load_dwordx4 v[146:149], v[220:221], off offset:256
	v_add_co_u32_e32 v220, vcc, 0x40000, v220
	s_waitcnt lgkmcnt(6)
	v_mfma_f32_32x32x16_bf16 v[98:113], v[174:177], v[214:217], v[98:113]
	s_waitcnt vmcnt(7)
	ds_write_b128 v240, v[150:153] offset:55296
	v_addc_co_u32_e32 v221, vcc, 0, v221, vcc
	global_load_dwordx4 v[150:153], v[234:235], off offset:256
	v_add_co_u32_e32 v234, vcc, 0x40000, v234
	v_mfma_f32_32x32x16_bf16 v[82:97], v[182:185], v[206:209], v[82:97]
	s_waitcnt vmcnt(7)
	ds_write_b128 v240, v[154:157] offset:27648
	v_addc_co_u32_e32 v235, vcc, 0, v235, vcc
	global_load_dwordx4 v[154:157], v[220:221], off offset:256
	v_mfma_f32_32x32x16_bf16 v[66:81], v[182:185], v[214:217], v[66:81]
	s_waitcnt vmcnt(7)
	ds_write_b128 v240, v[158:161] offset:64512
	global_load_dwordx4 v[158:161], v[234:235], off offset:256
	v_mfma_f32_32x32x16_bf16 v[50:65], v[190:193], v[206:209], v[50:65]
	v_mfma_f32_32x32x16_bf16 v[34:49], v[190:193], v[214:217], v[34:49]
	s_waitcnt lgkmcnt(8)
	v_mfma_f32_32x32x16_bf16 v[18:33], v[198:201], v[206:209], v[18:33]
	v_mfma_f32_32x32x16_bf16 v[2:17], v[198:201], v[214:217], v[2:17]
	s_setprio 0
	s_add_u32 s0, s0, 0x80
	s_addc_u32 s1, s1, 0
	s_add_i32 s4, s4, 2
	s_add_i32 s2, s2, 1
	s_add_i32 s52, s4, -2
	s_and_b32 s52, s52, 2
	s_mul_i32 s52, s52, 0x9000
	v_add_u32_e32 v0, s52, v164
	v_add_u32_e32 v165, s52, v163
	s_cmp_gt_u32 s2, 29
	s_waitcnt lgkmcnt(0)
	s_barrier
	s_cbranch_scc0 .Lrot119_body

; #define MFMA32(a, b, c) __builtin_amdgcn_mfma_f32_32x32x16_bf16((a), (b), (c), 0, 0, 0)
; #define G_LOAD(KT) do { const int k0_ = (KT) << 6; _Pragma("unroll") for (int p = 0; p < 4; ++p) { \
;     ra[p] = *(const u32x4*)(ap + (size_t)(64 * p) * lda + k0_); rb[p] = *(const u32x4*)(bp + (size_t)(64 * p) * ldb + k0_); } } while (0)
; template <bool SWAP, bool SSQ, bool ZERO = true>
; DI void gemm_main(const u16* __restrict__ A, int lda, const u16* __restrict__ Bt, int ldb, int K, char* lds,
;                   f32x16 (&acc)[4][2], float* rs_lds) {
;     ...
;   for (int kt = 0; kt < nk; ++kt) {
;     const int st = (kt & 1) * 2 * G_TILE;
;     {
;       bf16x8 fa[2][4], fb[2][2];
; #pragma unroll
;       for (int i = 0; i < 4; ++i) fa[0][i] = *(const bf16x8*)(abase + st + i * 32 * GS);
; #pragma unroll
;       for (int i = 0; i < 2; ++i) fb[0][i] = *(const bf16x8*)(bbase + st + i * 32 * GS);
; #pragma unroll
;       for (int ks = 0; ks < 4; ++ks) {
;         if (ks + 1 < 4) {
; #pragma unroll
;           for (int i = 0; i < 4; ++i) fa[(ks + 1) & 1][i] = *(const bf16x8*)(abase + st + i * 32 * GS + (ks + 1) * 32);
; #pragma unroll
;           for (int i = 0; i < 2; ++i) fb[(ks + 1) & 1][i] = *(const bf16x8*)(bbase + st + i * 32 * GS + (ks + 1) * 32);
;         }
;         __builtin_amdgcn_sched_barrier(0);
;         __builtin_amdgcn_s_setprio(1);
; #pragma unroll
;         for (int mt = 0; mt < 4; ++mt)
; #pragma unroll
;           for (int nt = 0; nt < 2; ++nt)
;             acc[mt][nt] = SWAP ? MFMA32(fb[ks & 1][nt], fa[ks & 1][mt], acc[mt][nt]) : MFMA32(fa[ks & 1][mt], fb[ks & 1][nt], acc[mt][nt]);
;         __builtin_amdgcn_s_setprio(0);
;         __builtin_amdgcn_sched_barrier(0);
;       }
;     }
;     if (kt + 1 < nk) G_WRITE((kt + 1) & 1);
;     if (kt + 2 < nk) G_LOAD(kt + 2);
;     __syncthreads();
;   }
.Lrot292_body:
	ds_read_b128 v[214:217], v240 offset:36864
	ds_read_b128 v[182:185], v177
	ds_read_b128 v[232:235], v240 offset:41472
	ds_read_b128 v[190:193], v177 offset:4608
	ds_read_b128 v[198:201], v177 offset:9216
	ds_read_b128 v[206:209], v177 offset:13824
	s_setprio 1
	s_waitcnt lgkmcnt(4)
	v_mfma_f32_32x32x16_bf16 v[114:129], v[214:217], v[182:185], v[114:129]
	ds_read_b128 v[218:221], v240 offset:36896
	s_waitcnt lgkmcnt(4)
	v_mfma_f32_32x32x16_bf16 v[98:113], v[232:235], v[182:185], v[98:113]
	ds_read_b128 v[186:189], v177 offset:32
	ds_read_b128 v[182:185], v177 offset:64
	s_waitcnt lgkmcnt(5)
	v_mfma_f32_32x32x16_bf16 v[82:97], v[214:217], v[190:193], v[82:97]
	ds_read_b128 v[236:239], v240 offset:41504
	v_mfma_f32_32x32x16_bf16 v[66:81], v[232:235], v[190:193], v[66:81]
	ds_read_b128 v[194:197], v177 offset:4640
	ds_read_b128 v[190:193], v177 offset:4672
	s_waitcnt lgkmcnt(7)
	v_mfma_f32_32x32x16_bf16 v[50:65], v[214:217], v[198:201], v[50:65]
	ds_read_b128 v[202:205], v177 offset:9248
	v_mfma_f32_32x32x16_bf16 v[34:49], v[232:235], v[198:201], v[34:49]
	ds_read_b128 v[210:213], v177 offset:13856
	ds_read_b128 v[198:201], v177 offset:9280
	s_waitcnt lgkmcnt(9)
	v_mfma_f32_32x32x16_bf16 v[18:33], v[214:217], v[206:209], v[18:33]
	ds_read_b128 v[214:217], v240 offset:36928
	v_mfma_f32_32x32x16_bf16 v[2:17], v[232:235], v[206:209], v[2:17]
	ds_read_b128 v[232:235], v240 offset:41536
	ds_read_b128 v[206:209], v177 offset:13888
	s_setprio 0
	s_setprio 1
	s_waitcnt lgkmcnt(10)
	v_mfma_f32_32x32x16_bf16 v[114:129], v[218:221], v[186:189], v[114:129]
	s_waitcnt lgkmcnt(8)
	v_mfma_f32_32x32x16_bf16 v[98:113], v[236:239], v[186:189], v[98:113]
	ds_read_b128 v[186:189], v177 offset:96
	s_waitcnt lgkmcnt(8)
	v_mfma_f32_32x32x16_bf16 v[82:97], v[218:221], v[194:197], v[82:97]
	v_mfma_f32_32x32x16_bf16 v[66:81], v[236:239], v[194:197], v[66:81]
	ds_read_b128 v[194:197], v177 offset:4704
	s_waitcnt lgkmcnt(7)
	v_mfma_f32_32x32x16_bf16 v[50:65], v[218:221], v[202:205], v[50:65]
	v_mfma_f32_32x32x16_bf16 v[34:49], v[236:239], v[202:205], v[34:49]
	ds_read_b128 v[202:205], v177 offset:9312
	s_waitcnt lgkmcnt(7)
	v_mfma_f32_32x32x16_bf16 v[18:33], v[218:221], v[210:213], v[18:33]
	ds_read_b128 v[218:221], v240 offset:36960
	v_mfma_f32_32x32x16_bf16 v[2:17], v[236:239], v[210:213], v[2:17]
	ds_read_b128 v[236:239], v240 offset:41568
	ds_read_b128 v[210:213], v177 offset:13920
	s_setprio 0
	s_setprio 1
	s_waitcnt lgkmcnt(8)
	v_mfma_f32_32x32x16_bf16 v[114:129], v[214:217], v[182:185], v[114:129]
	s_waitcnt lgkmcnt(7)
	v_mfma_f32_32x32x16_bf16 v[98:113], v[232:235], v[182:185], v[98:113]
	v_mfma_f32_32x32x16_bf16 v[82:97], v[214:217], v[190:193], v[82:97]
	v_mfma_f32_32x32x16_bf16 v[66:81], v[232:235], v[190:193], v[66:81]
	s_and_b32 s4, s85, 2
	s_mul_i32 s4, s4, 0x9000
	v_add_u32_e32 v242, s4, v174
	v_lshl_add_u64 v[244:245], v[180:181], 0, s[82:83]
	v_lshl_add_u64 v[246:247], v[178:179], 0, s[82:83]
	v_mfma_f32_32x32x16_bf16 v[50:65], v[214:217], v[198:201], v[50:65]
	s_waitcnt vmcnt(7)
	ds_write_b128 v242, v[130:133]
	global_load_dwordx4 v[130:133], v[244:245], off offset:256
	v_add_co_u32_e32 v244, vcc, 0x40000, v244
	v_mfma_f32_32x32x16_bf16 v[34:49], v[232:235], v[198:201], v[34:49]
	s_waitcnt vmcnt(7)
	ds_write_b128 v242, v[134:137] offset:36864
	v_addc_co_u32_e32 v245, vcc, 0, v245, vcc
	global_load_dwordx4 v[134:137], v[246:247], off offset:256
	v_add_co_u32_e32 v246, vcc, 0x40000, v246
	s_waitcnt lgkmcnt(8)
	v_mfma_f32_32x32x16_bf16 v[18:33], v[214:217], v[206:209], v[18:33]
	s_waitcnt vmcnt(7)
	ds_write_b128 v242, v[138:141] offset:9216
	v_addc_co_u32_e32 v247, vcc, 0, v247, vcc
	global_load_dwordx4 v[138:141], v[244:245], off offset:256
	v_add_co_u32_e32 v244, vcc, 0x40000, v244
	v_mfma_f32_32x32x16_bf16 v[2:17], v[232:235], v[206:209], v[2:17]
	s_waitcnt vmcnt(7)
	ds_write_b128 v242, v[142:145] offset:46080
	v_addc_co_u32_e32 v245, vcc, 0, v245, vcc
	global_load_dwordx4 v[142:145], v[246:247], off offset:256
	v_add_co_u32_e32 v246, vcc, 0x40000, v246
	s_setprio 0
	s_setprio 1
	s_waitcnt lgkmcnt(6)
	v_mfma_f32_32x32x16_bf16 v[114:129], v[218:221], v[186:189], v[114:129]
	s_waitcnt vmcnt(7)
	ds_write_b128 v242, v[146:149] offset:18432
	v_addc_co_u32_e32 v247, vcc, 0, v247, vcc
	global_load_dwordx4 v[146:149], v[244:245], off offset:256
	v_add_co_u32_e32 v244, vcc, 0x40000, v244
	s_waitcnt lgkmcnt(6)
	v_mfma_f32_32x32x16_bf16 v[98:113], v[236:239], v[186:189], v[98:113]
	s_waitcnt vmcnt(7)
	ds_write_b128 v242, v[150:153] offset:55296
	v_addc_co_u32_e32 v245, vcc, 0, v245, vcc
	global_load_dwordx4 v[150:153], v[246:247], off offset:256
	v_add_co_u32_e32 v246, vcc, 0x40000, v246
	v_mfma_f32_32x32x16_bf16 v[82:97], v[218:221], v[194:197], v[82:97]
	s_waitcnt vmcnt(7)
	ds_write_b128 v242, v[154:157] offset:27648
	v_addc_co_u32_e32 v247, vcc, 0, v247, vcc
	global_load_dwordx4 v[154:157], v[244:245], off offset:256
	v_mfma_f32_32x32x16_bf16 v[66:81], v[236:239], v[194:197], v[66:81]
	s_waitcnt vmcnt(7)
	ds_write_b128 v242, v[158:161] offset:64512
	global_load_dwordx4 v[158:161], v[246:247], off offset:256
	v_mfma_f32_32x32x16_bf16 v[50:65], v[218:221], v[202:205], v[50:65]
	v_mfma_f32_32x32x16_bf16 v[34:49], v[236:239], v[202:205], v[34:49]
	s_waitcnt lgkmcnt(8)
	v_mfma_f32_32x32x16_bf16 v[18:33], v[218:221], v[210:213], v[18:33]
	v_mfma_f32_32x32x16_bf16 v[2:17], v[236:239], v[210:213], v[2:17]
	s_setprio 0
	s_add_u32 s82, s82, 0x80
	s_addc_u32 s83, s83, 0
	s_add_i32 s85, s85, 2
	s_add_i32 s86, s86, 1
	s_add_i32 s4, s85, -2
	s_and_b32 s4, s4, 2
	s_mul_i32 s4, s4, 0x9000
	v_add_u32_e32 v177, s4, v176
	v_add_u32_e32 v240, s4, v175
	s_cmp_gt_u32 s86, 29
	s_waitcnt lgkmcnt(0)
	s_barrier
	s_cbranch_scc0 .Lrot292_body
